# rows phase: xor-1/2/4/8 lane exchanges of the reductions as DPP moves (no LDS round trip), 33 of 66 ds_bpermute
# speedup vs baseline: 1.0089x; 1.0089x over previous
.LBB0_463:
	s_waitcnt vmcnt(11)
	v_and_b32_e32 v121, 0xffff0000, v52
	s_waitcnt vmcnt(10)
	v_and_b32_e32 v125, 0xffff0000, v50
	v_lshlrev_b32_e32 v120, 16, v52
	v_lshlrev_b32_e32 v124, 16, v50
	v_lshlrev_b32_e32 v122, 16, v53
	v_lshlrev_b32_e32 v126, 16, v51
	v_mul_f32_e32 v86, v121, v121
	v_mul_f32_e32 v87, v125, v125
	v_and_b32_e32 v123, 0xffff0000, v53
	v_and_b32_e32 v127, 0xffff0000, v51
	v_fma_f32 v84, v120, v120, v86
	v_fma_f32 v85, v124, v124, v87
	v_fma_f32 v84, v122, v122, v84
	v_fma_f32 v85, v126, v126, v85
	s_waitcnt vmcnt(9)
	v_and_b32_e32 v129, 0xffff0000, v56
	s_waitcnt vmcnt(8)
	v_and_b32_e32 v133, 0xffff0000, v54
	v_fma_f32 v84, v123, v123, v84
	v_fma_f32 v85, v127, v127, v85
	v_lshlrev_b32_e32 v128, 16, v56
	v_lshlrev_b32_e32 v132, 16, v54
	v_lshlrev_b32_e32 v130, 16, v57
	v_lshlrev_b32_e32 v134, 16, v55
	v_mul_f32_e32 v88, v133, v133
	v_mul_f32_e32 v89, v129, v129
	v_and_b32_e32 v131, 0xffff0000, v57
	v_and_b32_e32 v135, 0xffff0000, v55
	v_fma_f32 v86, v132, v132, v88
	v_fma_f32 v87, v128, v128, v89
	v_fma_f32 v86, v134, v134, v86
	v_fma_f32 v87, v130, v130, v87
	v_add_f32_e32 v84, v84, v85
	v_fma_f32 v86, v135, v135, v86
	v_fma_f32 v87, v131, v131, v87
	v_add_f32_e32 v84, v87, v84
	v_add_f32_e32 v84, v86, v84
	ds_bpermute_b32 v85, v249, v84
	s_add_i32 s2, s50, 0xffff8000
	s_waitcnt lgkmcnt(0)
	v_add_f32_e32 v84, v84, v85
	ds_bpermute_b32 v85, v248, v84
	s_mov_b32 s60, s83
	s_cmpk_gt_i32 s50, 0x7fff
	s_waitcnt lgkmcnt(0)
	v_add_f32_e32 v84, v84, v85
	s_nop 1
	v_mov_b32_dpp v85, v84 row_ror:8 row_mask:0xf bank_mask:0xf
	s_mov_b32 s61, s84
	s_mov_b32 s18, s85
	s_waitcnt lgkmcnt(0)
	v_add_f32_e32 v84, v84, v85
	s_nop 1
	v_mov_b32_dpp v85, v84 row_half_mirror row_mask:0xf bank_mask:0xf
	s_nop 1
	v_mov_b32_dpp v85, v85 quad_perm:[3,2,1,0] row_mask:0xf bank_mask:0xf
	s_cselect_b32 s3, 0, s51
	s_cselect_b32 s2, s2, s50
	s_waitcnt lgkmcnt(0)
	v_add_f32_e32 v84, v84, v85
	s_nop 1
	v_mov_b32_dpp v85, v84 quad_perm:[2,3,0,1] row_mask:0xf bank_mask:0xf
	s_cselect_b32 s19, s18, s61
	s_mov_b32 s18, s86
	s_waitcnt lgkmcnt(0)
	v_add_f32_e32 v104, v84, v85
	s_nop 1
	v_mov_b32_dpp v105, v104 quad_perm:[1,0,3,2] row_mask:0xf bank_mask:0xf
	s_cselect_b32 s18, s18, s60
	s_lshl_b64 s[2:3], s[2:3], 12
	s_add_u32 s18, s18, s2
	s_addc_u32 s19, s19, s3
	s_and_b32 s2, s1, 0xfffff000
	s_waitcnt lgkmcnt(0)
	v_add_f32_e32 v104, v104, v105
	v_add_u32_e32 v103, s2, v100
	v_fmamk_f32 v104, v104, 0x3a800000, v218
	s_mov_b32 s2, 0x800000
	v_mul_f32_e32 v105, 0x4b800000, v104
	v_cmp_gt_f32_e32 vcc, s2, v104
	ds_read_b128 v[84:87], v100 offset:32768
	ds_read_b128 v[88:91], v100 offset:33792
	ds_read_b128 v[92:95], v103 offset:40960
	ds_read_b128 v[96:99], v103 offset:41984
	v_cndmask_b32_e32 v104, v104, v105, vcc
	v_rsq_f32_e32 v136, v104
	ds_read_b128 v[104:107], v100 offset:34816
	ds_read_b128 v[108:111], v100 offset:35840
	ds_read_b128 v[112:115], v103 offset:43008
	ds_read_b128 v[116:119], v103 offset:44032
	s_mov_b32 s62, s87
	s_mov_b32 s63, s88
	v_mul_f32_e32 v103, 0x45800000, v136
	v_cndmask_b32_e32 v136, v136, v103, vcc
	v_pk_mul_f32 v[120:121], v[136:137], v[120:121] op_sel_hi:[0,1]
	s_waitcnt lgkmcnt(7)
	v_pk_mul_f32 v[84:85], v[84:85], v[120:121]
	s_waitcnt lgkmcnt(5)
	v_pk_fma_f32 v[0:1], v[92:93], v[84:85], v[0:1]
	v_pk_mul_f32 v[84:85], v[136:137], v[122:123] op_sel_hi:[0,1]
	v_pk_mul_f32 v[84:85], v[86:87], v[84:85]
	s_nop 0
	v_pk_fma_f32 v[2:3], v[94:95], v[84:85], v[2:3]
	v_pk_mul_f32 v[84:85], v[136:137], v[124:125] op_sel_hi:[0,1]
	v_pk_mul_f32 v[84:85], v[88:89], v[84:85]
	global_store_dwordx4 v8, v[0:3], s[18:19] nt
	s_waitcnt lgkmcnt(4)
	v_pk_fma_f32 v[4:5], v[96:97], v[84:85], v[4:5]
	v_pk_mul_f32 v[84:85], v[136:137], v[126:127] op_sel_hi:[0,1]
	v_pk_mul_f32 v[84:85], v[90:91], v[84:85]
	s_nop 0
	v_pk_fma_f32 v[6:7], v[98:99], v[84:85], v[6:7]
	v_pk_mul_f32 v[84:85], v[136:137], v[128:129] op_sel_hi:[0,1]
	s_waitcnt lgkmcnt(3)
	v_pk_mul_f32 v[84:85], v[104:105], v[84:85]
	global_store_dwordx4 v8, v[4:7], s[18:19] offset:1024 nt
	s_waitcnt lgkmcnt(1)
	v_pk_fma_f32 v[10:11], v[112:113], v[84:85], v[10:11]
	v_pk_mul_f32 v[84:85], v[136:137], v[130:131] op_sel_hi:[0,1]
	v_pk_mul_f32 v[84:85], v[106:107], v[84:85]
	s_nop 0
	v_pk_fma_f32 v[12:13], v[114:115], v[84:85], v[12:13]
	v_pk_mul_f32 v[84:85], v[136:137], v[132:133] op_sel_hi:[0,1]
	v_pk_mul_f32 v[84:85], v[84:85], v[108:109]
	global_store_dwordx4 v8, v[10:13], s[18:19] offset:2048 nt
	s_waitcnt lgkmcnt(0)
	v_pk_fma_f32 v[14:15], v[116:117], v[84:85], v[14:15]
	v_pk_mul_f32 v[84:85], v[136:137], v[134:135] op_sel_hi:[0,1]
	v_pk_mul_f32 v[84:85], v[84:85], v[110:111]
	s_nop 0
	v_pk_fma_f32 v[16:17], v[118:119], v[84:85], v[16:17]
	global_store_dwordx4 v8, v[14:17], s[18:19] offset:3072 nt
.LBB0_464:
	s_mov_b32 s2, s89
	s_mov_b32 s3, s90
	s_andn2_b64 vcc, exec, s[2:3]
	s_nop 0
	v_cndmask_b32_e64 v84, 0, 1, s[2:3]
	v_cmp_ne_u32_e64 s[48:49], 1, v84
	s_cbranch_vccnz .LBB0_468
	s_waitcnt vmcnt(10)
	v_mul_f32_e32 v86, v5, v5
	v_mul_f32_e32 v87, v1, v1
	s_waitcnt vmcnt(8)
	v_fma_f32 v84, v4, v4, v86
	v_fma_f32 v85, v0, v0, v87
	v_fma_f32 v84, v6, v6, v84
	v_fma_f32 v85, v2, v2, v85
	v_fma_f32 v84, v7, v7, v84
	v_fma_f32 v85, v3, v3, v85
	v_mul_f32_e32 v88, v15, v15
	v_mul_f32_e32 v89, v11, v11
	v_add_f32_e32 v84, v84, v85
	v_fma_f32 v86, v14, v14, v88
	v_fma_f32 v87, v10, v10, v89
	v_fma_f32 v86, v16, v16, v86
	v_fma_f32 v87, v12, v12, v87
	v_fma_f32 v86, v17, v17, v86
	v_fma_f32 v87, v13, v13, v87
	v_add_f32_e32 v84, v87, v84
	v_add_f32_e32 v84, v86, v84
	s_mov_b32 s2, 0x800000
	s_and_b32 s1, s1, 0xfffff000
	ds_bpermute_b32 v86, v249, v84
	v_add_u32_e32 v98, s1, v101
	ds_read_b128 v[104:107], v98
	s_mov_b32 s60, s83
	s_mov_b32 s62, s87
	s_waitcnt lgkmcnt(1)
	v_add_f32_e32 v84, v84, v86
	s_mov_b32 s63, s88
	s_mov_b32 s61, s84
	ds_bpermute_b32 v86, v248, v84
	s_waitcnt lgkmcnt(0)
	v_add_f32_e32 v84, v84, v86
	s_nop 1
	s_nop 1
	v_mov_b32_dpp v86, v84 row_ror:8 row_mask:0xf bank_mask:0xf
	s_waitcnt lgkmcnt(0)
	v_add_f32_e32 v84, v84, v86
	s_nop 1
	s_nop 1
	v_mov_b32_dpp v86, v84 row_half_mirror row_mask:0xf bank_mask:0xf
	s_nop 1
	v_mov_b32_dpp v86, v86 quad_perm:[3,2,1,0] row_mask:0xf bank_mask:0xf
	s_waitcnt lgkmcnt(0)
	v_add_f32_e32 v84, v84, v86
	s_nop 1
	s_nop 1
	v_mov_b32_dpp v86, v84 quad_perm:[2,3,0,1] row_mask:0xf bank_mask:0xf
	s_waitcnt lgkmcnt(0)
	v_add_f32_e32 v84, v84, v86
	s_nop 1
	s_nop 1
	v_mov_b32_dpp v85, v84 quad_perm:[1,0,3,2] row_mask:0xf bank_mask:0xf
	ds_read_b128 v[86:89], v100 offset:36864
	s_waitcnt lgkmcnt(1)
	v_add_f32_e32 v84, v84, v85
	v_fmamk_f32 v84, v84, 0x3a800000, v218
	v_cmp_gt_f32_e32 vcc, s2, v84
	v_mul_f32_e32 v85, 0x4b800000, v84
	s_nop 0
	v_cndmask_b32_e32 v84, v84, v85, vcc
	v_rsq_f32_e32 v84, v84
	s_nop 0
	v_mul_f32_e32 v85, 0x45800000, v84
	v_cndmask_b32_e32 v84, v84, v85, vcc
	v_add_u32_e32 v85, s1, v102
	ds_read_b128 v[108:111], v85
	v_pk_mul_f32 v[90:91], v[0:1], v[84:85] op_sel_hi:[1,0]
	s_mov_b32 s1, 0xb00000
	s_waitcnt lgkmcnt(1)
	v_pk_mul_f32 v[86:87], v[86:87], v[90:91]
	v_pk_add_f32 v[90:91], v[104:105], 1.0 op_sel_hi:[1,0]
	v_pk_mul_f32 v[118:119], v[4:5], v[84:85] op_sel_hi:[1,0]
	s_waitcnt lgkmcnt(0)
	v_pk_fma_f32 v[112:113], v[90:91], v[86:87], v[108:109]
	v_pk_mul_f32 v[86:87], v[2:3], v[84:85] op_sel_hi:[1,0]
	s_nop 0
	v_pk_mul_f32 v[86:87], v[88:89], v[86:87]
	v_pk_add_f32 v[88:89], v[106:107], 1.0 op_sel_hi:[1,0]
	s_nop 0
	v_pk_fma_f32 v[110:111], v[88:89], v[86:87], v[110:111]
	v_lshl_add_u64 v[86:87], s[62:63], 0, v[70:71]
	v_add_co_u32_e32 v86, vcc, s1, v86
	v_cvt_pk_bf16_f32 v88, v112, v113
	v_cvt_pk_bf16_f32 v89, v110, v111
	v_addc_co_u32_e32 v87, vcc, 0, v87, vcc
	global_store_dwordx2 v[86:87], v[88:89], off
	ds_read_b128 v[88:91], v100
	s_waitcnt lgkmcnt(0)
	v_mul_f32_e32 v89, v89, v113
	v_fmac_f32_e32 v89, v88, v112
	v_fmac_f32_e32 v89, v90, v110
	v_fmac_f32_e32 v89, v91, v111
	v_add_f32_e32 v107, 0, v89
	ds_read_b128 v[88:91], v100 offset:4096
	s_waitcnt lgkmcnt(0)
	v_mul_f32_e32 v89, v89, v113
	v_fmac_f32_e32 v89, v88, v112
	v_fmac_f32_e32 v89, v90, v110
	v_fmac_f32_e32 v89, v91, v111
	v_add_f32_e32 v109, 0, v89
	ds_read_b128 v[88:91], v100 offset:8192
	s_waitcnt lgkmcnt(0)
	v_mul_f32_e32 v89, v89, v113
	v_fmac_f32_e32 v89, v88, v112
	v_fmac_f32_e32 v89, v90, v110
	v_fmac_f32_e32 v89, v91, v111
	v_add_f32_e32 v108, 0, v89
	ds_read_b128 v[88:91], v100 offset:12288
	s_waitcnt lgkmcnt(0)
	v_mul_f32_e32 v89, v89, v113
	v_fmac_f32_e32 v89, v88, v112
	v_fmac_f32_e32 v89, v90, v110
	v_fmac_f32_e32 v89, v91, v111
	v_add_f32_e32 v106, 0, v89
	ds_read_b128 v[88:91], v100 offset:16384
	s_waitcnt lgkmcnt(0)
	v_mul_f32_e32 v89, v89, v113
	v_fmac_f32_e32 v89, v88, v112
	v_fmac_f32_e32 v89, v90, v110
	v_fmac_f32_e32 v89, v91, v111
	v_add_f32_e32 v105, 0, v89
	ds_read_b128 v[88:91], v100 offset:20480
	s_waitcnt lgkmcnt(0)
	v_mul_f32_e32 v89, v89, v113
	v_fmac_f32_e32 v89, v88, v112
	v_fmac_f32_e32 v89, v90, v110
	v_fmac_f32_e32 v89, v91, v111
	v_add_f32_e32 v104, 0, v89
	ds_read_b128 v[88:91], v100 offset:24576
	s_waitcnt lgkmcnt(0)
	v_mul_f32_e32 v89, v89, v113
	v_fmac_f32_e32 v89, v88, v112
	v_fmac_f32_e32 v89, v90, v110
	v_fmac_f32_e32 v89, v91, v111
	v_add_f32_e32 v103, 0, v89
	ds_read_b128 v[88:91], v100 offset:28672
	s_waitcnt lgkmcnt(0)
	v_mul_f32_e32 v89, v113, v89
	v_fmac_f32_e32 v89, v112, v88
	v_fmac_f32_e32 v89, v110, v90
	v_fmac_f32_e32 v89, v111, v91
	v_add_f32_e32 v99, 0, v89
	ds_read_b128 v[88:91], v100 offset:37888
	ds_read_b128 v[110:113], v98 offset:1024
	ds_read_b128 v[114:117], v85 offset:1024
	s_waitcnt lgkmcnt(2)
	v_pk_mul_f32 v[88:89], v[118:119], v[88:89]
	s_waitcnt lgkmcnt(1)
	v_pk_add_f32 v[110:111], v[110:111], 1.0 op_sel_hi:[1,0]
	s_waitcnt lgkmcnt(0)
	v_pk_fma_f32 v[88:89], v[88:89], v[110:111], v[114:115]
	v_pk_mul_f32 v[110:111], v[6:7], v[84:85] op_sel_hi:[1,0]
	s_nop 0
	v_pk_mul_f32 v[90:91], v[110:111], v[90:91]
	v_pk_add_f32 v[110:111], v[112:113], 1.0 op_sel_hi:[1,0]
	s_nop 0
	v_pk_fma_f32 v[90:91], v[90:91], v[110:111], v[116:117]
	v_cvt_pk_bf16_f32 v110, v88, v89
	v_cvt_pk_bf16_f32 v111, v90, v91
	global_store_dwordx2 v[86:87], v[110:111], off offset:512
	ds_read_b128 v[110:113], v100 offset:1024
	s_waitcnt lgkmcnt(0)
	v_mul_f32_e32 v111, v89, v111
	v_fmac_f32_e32 v111, v88, v110
	v_fmac_f32_e32 v111, v90, v112
	v_fmac_f32_e32 v111, v91, v113
	v_add_f32_e32 v107, v107, v111
	ds_read_b128 v[110:113], v100 offset:5120
	s_waitcnt lgkmcnt(0)
	v_mul_f32_e32 v111, v89, v111
	v_fmac_f32_e32 v111, v88, v110
	v_fmac_f32_e32 v111, v90, v112
	v_fmac_f32_e32 v111, v91, v113
	v_add_f32_e32 v116, v109, v111
	ds_read_b128 v[110:113], v100 offset:9216
	s_waitcnt lgkmcnt(0)
	v_mul_f32_e32 v109, v89, v111
	v_fmac_f32_e32 v109, v88, v110
	v_fmac_f32_e32 v109, v90, v112
	v_fmac_f32_e32 v109, v91, v113
	v_add_f32_e32 v117, v108, v109
	ds_read_b128 v[108:111], v100 offset:13312
	s_waitcnt lgkmcnt(0)
	v_mul_f32_e32 v109, v89, v109
	v_fmac_f32_e32 v109, v88, v108
	v_fmac_f32_e32 v109, v90, v110
	v_fmac_f32_e32 v109, v91, v111
	v_add_f32_e32 v106, v106, v109
	ds_read_b128 v[108:111], v100 offset:17408
	s_waitcnt lgkmcnt(0)
	v_mul_f32_e32 v109, v89, v109
	v_fmac_f32_e32 v109, v88, v108
	v_fmac_f32_e32 v109, v90, v110
	v_fmac_f32_e32 v109, v91, v111
	v_add_f32_e32 v118, v105, v109
	ds_read_b128 v[108:111], v100 offset:21504
	s_waitcnt lgkmcnt(0)
	v_mul_f32_e32 v105, v89, v109
	v_fmac_f32_e32 v105, v88, v108
	v_fmac_f32_e32 v105, v90, v110
	v_fmac_f32_e32 v105, v91, v111
	ds_read_b128 v[108:111], v100 offset:25600
	v_add_f32_e32 v119, v104, v105
	s_waitcnt lgkmcnt(0)
	v_mul_f32_e32 v104, v89, v109
	v_fmac_f32_e32 v104, v88, v108
	v_fmac_f32_e32 v104, v90, v110
	v_fmac_f32_e32 v104, v91, v111
	ds_read_b128 v[108:111], v100 offset:29696
	v_add_f32_e32 v120, v103, v104
	v_pk_mul_f32 v[104:105], v[10:11], v[84:85] op_sel_hi:[1,0]
	s_waitcnt lgkmcnt(0)
	v_mul_f32_e32 v89, v89, v109
	v_fmac_f32_e32 v89, v88, v108
	v_fmac_f32_e32 v89, v90, v110
	v_fmac_f32_e32 v89, v91, v111
	v_add_f32_e32 v121, v99, v89
	ds_read_b128 v[88:91], v100 offset:38912
	ds_read_b128 v[108:111], v98 offset:2048
	ds_read_b128 v[112:115], v85 offset:2048
	s_waitcnt lgkmcnt(2)
	v_pk_mul_f32 v[88:89], v[104:105], v[88:89]
	s_waitcnt lgkmcnt(1)
	v_pk_add_f32 v[104:105], v[108:109], 1.0 op_sel_hi:[1,0]
	s_waitcnt lgkmcnt(0)
	v_pk_fma_f32 v[112:113], v[88:89], v[104:105], v[112:113]
	v_pk_mul_f32 v[88:89], v[12:13], v[84:85] op_sel_hi:[1,0]
	s_nop 0
	v_pk_mul_f32 v[88:89], v[88:89], v[90:91]
	v_pk_add_f32 v[90:91], v[110:111], 1.0 op_sel_hi:[1,0]
	s_nop 0
	v_pk_fma_f32 v[110:111], v[88:89], v[90:91], v[114:115]
	v_cvt_pk_bf16_f32 v88, v112, v113
	v_cvt_pk_bf16_f32 v89, v110, v111
	global_store_dwordx2 v[86:87], v[88:89], off offset:1024
	ds_read_b128 v[88:91], v100 offset:2048
	s_waitcnt lgkmcnt(0)
	v_mul_f32_e32 v89, v113, v89
	v_fmac_f32_e32 v89, v112, v88
	v_fmac_f32_e32 v89, v110, v90
	v_fmac_f32_e32 v89, v111, v91
	v_add_f32_e32 v105, v107, v89
	ds_read_b128 v[88:91], v100 offset:6144
	s_waitcnt lgkmcnt(0)
	v_mul_f32_e32 v89, v113, v89
	v_fmac_f32_e32 v89, v112, v88
	v_fmac_f32_e32 v89, v110, v90
	v_fmac_f32_e32 v89, v111, v91
	v_add_f32_e32 v122, v116, v89
	ds_read_b128 v[88:91], v100 offset:10240
	s_waitcnt lgkmcnt(0)
	v_mul_f32_e32 v89, v113, v89
	v_fmac_f32_e32 v89, v112, v88
	v_fmac_f32_e32 v89, v110, v90
	v_fmac_f32_e32 v89, v111, v91
	v_add_f32_e32 v123, v117, v89
	ds_read_b128 v[88:91], v100 offset:14336
	s_waitcnt lgkmcnt(0)
	v_mul_f32_e32 v89, v113, v89
	v_fmac_f32_e32 v89, v112, v88
	v_fmac_f32_e32 v89, v110, v90
	v_fmac_f32_e32 v89, v111, v91
	v_add_f32_e32 v104, v106, v89
	ds_read_b128 v[88:91], v100 offset:18432
	ds_read_b128 v[106:109], v100 offset:30720
	s_waitcnt lgkmcnt(1)
	v_mul_f32_e32 v89, v113, v89
	v_fmac_f32_e32 v89, v112, v88
	v_fmac_f32_e32 v89, v110, v90
	v_fmac_f32_e32 v89, v111, v91
	v_add_f32_e32 v103, v118, v89
	ds_read_b128 v[88:91], v100 offset:22528
	s_waitcnt lgkmcnt(0)
	v_mul_f32_e32 v89, v113, v89
	v_fmac_f32_e32 v89, v112, v88
	v_fmac_f32_e32 v89, v110, v90
	v_fmac_f32_e32 v89, v111, v91
	v_add_f32_e32 v99, v119, v89
	ds_read_b128 v[88:91], v100 offset:26624
	s_waitcnt lgkmcnt(0)
	v_mul_f32_e32 v89, v113, v89
	v_fmac_f32_e32 v89, v112, v88
	v_mul_f32_e32 v88, v113, v107
	v_fmac_f32_e32 v88, v112, v106
	v_fmac_f32_e32 v89, v110, v90
	v_fmac_f32_e32 v88, v110, v108
	v_fmac_f32_e32 v89, v111, v91
	v_fmac_f32_e32 v88, v111, v109
	ds_read_b128 v[106:109], v100 offset:39936
	ds_read_b128 v[110:113], v98 offset:3072
	ds_read_b128 v[114:117], v85 offset:3072
	v_add_f32_e32 v91, v120, v89
	v_add_f32_e32 v90, v121, v88
	v_pk_mul_f32 v[88:89], v[14:15], v[84:85] op_sel_hi:[1,0]
	v_pk_mul_f32 v[84:85], v[16:17], v[84:85] op_sel_hi:[1,0]
	s_waitcnt lgkmcnt(2)
	v_pk_mul_f32 v[88:89], v[88:89], v[106:107]
	s_waitcnt lgkmcnt(1)
	v_pk_add_f32 v[106:107], v[110:111], 1.0 op_sel_hi:[1,0]
	v_pk_mul_f32 v[84:85], v[84:85], v[108:109]
	s_waitcnt lgkmcnt(0)
	v_pk_fma_f32 v[88:89], v[88:89], v[106:107], v[114:115]
	v_pk_add_f32 v[106:107], v[112:113], 1.0 op_sel_hi:[1,0]
	s_nop 0
	v_pk_fma_f32 v[84:85], v[84:85], v[106:107], v[116:117]
	v_cvt_pk_bf16_f32 v106, v88, v89
	v_cvt_pk_bf16_f32 v107, v84, v85
	global_store_dwordx2 v[86:87], v[106:107], off offset:1536
	ds_read_b128 v[106:109], v100 offset:3072
	s_waitcnt lgkmcnt(0)
	v_mul_f32_e32 v86, v89, v107
	v_fmac_f32_e32 v86, v88, v106
	v_fmac_f32_e32 v86, v84, v108
	v_fmac_f32_e32 v86, v85, v109
	ds_read_b128 v[106:109], v100 offset:7168
	v_add_f32_e32 v86, v105, v86
	s_waitcnt lgkmcnt(0)
	v_mul_f32_e32 v87, v89, v107
	v_fmac_f32_e32 v87, v88, v106
	v_fmac_f32_e32 v87, v84, v108
	v_fmac_f32_e32 v87, v85, v109
	ds_read_b128 v[106:109], v100 offset:11264
	v_add_f32_e32 v87, v122, v87
	s_waitcnt lgkmcnt(0)
	v_mul_f32_e32 v98, v89, v107
	v_fmac_f32_e32 v98, v88, v106
	v_fmac_f32_e32 v98, v84, v108
	v_fmac_f32_e32 v98, v85, v109
	ds_read_b128 v[106:109], v100 offset:15360
	v_add_f32_e32 v98, v123, v98
	s_waitcnt lgkmcnt(0)
	v_mul_f32_e32 v105, v89, v107
	v_fmac_f32_e32 v105, v88, v106
	v_fmac_f32_e32 v105, v84, v108
	v_fmac_f32_e32 v105, v85, v109
	v_add_f32_e32 v108, v104, v105
	ds_read_b128 v[104:107], v100 offset:19456
	s_waitcnt lgkmcnt(0)
	v_mul_f32_e32 v105, v89, v105
	v_fmac_f32_e32 v105, v88, v104
	v_fmac_f32_e32 v105, v84, v106
	v_fmac_f32_e32 v105, v85, v107
	v_add_f32_e32 v103, v103, v105
	ds_read_b128 v[104:107], v100 offset:23552
	s_waitcnt lgkmcnt(0)
	v_mul_f32_e32 v105, v89, v105
	v_fmac_f32_e32 v105, v88, v104
	v_fmac_f32_e32 v105, v84, v106
	v_fmac_f32_e32 v105, v85, v107
	v_add_f32_e32 v99, v99, v105
	ds_read_b128 v[104:107], v100 offset:27648
	s_waitcnt lgkmcnt(0)
	v_mul_f32_e32 v105, v89, v105
	v_fmac_f32_e32 v105, v88, v104
	v_fmac_f32_e32 v105, v84, v106
	v_fmac_f32_e32 v105, v85, v107
	v_add_f32_e32 v91, v91, v105
	ds_read_b128 v[104:107], v100 offset:31744
	s_waitcnt lgkmcnt(0)
	v_mul_f32_e32 v89, v89, v105
	v_fmac_f32_e32 v89, v88, v104
	v_fmac_f32_e32 v89, v84, v106
	v_fmac_f32_e32 v89, v85, v107
	v_cndmask_b32_e64 v85, v103, v86, s[40:41]
	v_cndmask_b32_e64 v86, v86, v103, s[40:41]
	ds_bpermute_b32 v86, v249, v86
	v_cndmask_b32_e64 v88, v98, v91, s[40:41]
	ds_bpermute_b32 v88, v249, v88
	v_add_f32_e32 v84, v90, v89
	s_waitcnt lgkmcnt(1)
	v_add_f32_e32 v85, v85, v86
	v_cndmask_b32_e64 v86, v99, v87, s[40:41]
	v_cndmask_b32_e64 v87, v87, v99, s[40:41]
	ds_bpermute_b32 v87, v249, v87
	s_waitcnt lgkmcnt(0)
	v_add_f32_e32 v86, v86, v87
	v_cndmask_b32_e64 v87, v91, v98, s[40:41]
	v_add_f32_e32 v87, v87, v88
	v_cndmask_b32_e64 v88, v84, v108, s[40:41]
	v_cndmask_b32_e64 v84, v108, v84, s[40:41]
	ds_bpermute_b32 v84, v249, v84
	s_waitcnt lgkmcnt(0)
	v_add_f32_e32 v84, v88, v84
	v_cndmask_b32_e64 v88, v87, v85, s[42:43]
	v_cndmask_b32_e64 v85, v85, v87, s[42:43]
	v_cndmask_b32_e64 v87, v84, v86, s[42:43]
	v_cndmask_b32_e64 v84, v86, v84, s[42:43]
	ds_bpermute_b32 v85, v248, v85
	ds_bpermute_b32 v84, v248, v84
	s_waitcnt lgkmcnt(1)
	v_add_f32_e32 v85, v88, v85
	s_waitcnt lgkmcnt(0)
	v_add_f32_e32 v84, v87, v84
	v_cndmask_b32_e64 v86, v84, v85, s[44:45]
	v_cndmask_b32_e64 v84, v85, v84, s[44:45]
	s_nop 1
	v_mov_b32_dpp v84, v84 row_ror:8 row_mask:0xf bank_mask:0xf
	s_waitcnt lgkmcnt(0)
	v_add_f32_e32 v84, v86, v84
	s_nop 1
	v_mov_b32_dpp v85, v84 row_half_mirror row_mask:0xf bank_mask:0xf
	s_nop 1
	v_mov_b32_dpp v85, v85 quad_perm:[3,2,1,0] row_mask:0xf bank_mask:0xf
	s_waitcnt lgkmcnt(0)
	v_add_f32_e32 v84, v84, v85
	s_nop 1
	v_mov_b32_dpp v85, v84 quad_perm:[2,3,0,1] row_mask:0xf bank_mask:0xf
	s_waitcnt lgkmcnt(0)
	v_add_f32_e32 v84, v84, v85
	ds_bpermute_b32 v85, v244, v84
	s_and_saveexec_b64 s[18:19], s[46:47]
	s_cbranch_execz .LBB0_467
	s_mov_b32 s60, s83
	s_mov_b32 s62, s87
	s_mov_b32 s63, s88
	s_waitcnt lgkmcnt(0)
	v_add_f32_e32 v86, v84, v85
	s_mov_b32 s61, s84
	v_lshl_add_u64 v[84:85], s[62:63], 0, v[68:69]
	global_store_dword v[84:85], v86, off

.LBB0_486:
	s_waitcnt vmcnt(11)
	v_and_b32_e32 v121, 0xffff0000, v60
	s_waitcnt vmcnt(10)
	v_and_b32_e32 v125, 0xffff0000, v58
	v_lshlrev_b32_e32 v120, 16, v60
	v_lshlrev_b32_e32 v124, 16, v58
	v_lshlrev_b32_e32 v122, 16, v61
	v_lshlrev_b32_e32 v126, 16, v59
	v_mul_f32_e32 v86, v121, v121
	v_mul_f32_e32 v87, v125, v125
	v_and_b32_e32 v123, 0xffff0000, v61
	v_and_b32_e32 v127, 0xffff0000, v59
	v_fma_f32 v84, v120, v120, v86
	v_fma_f32 v85, v124, v124, v87
	v_fma_f32 v84, v122, v122, v84
	v_fma_f32 v85, v126, v126, v85
	s_waitcnt vmcnt(9)
	v_and_b32_e32 v129, 0xffff0000, v74
	s_waitcnt vmcnt(8)
	v_and_b32_e32 v133, 0xffff0000, v72
	v_fma_f32 v84, v123, v123, v84
	v_fma_f32 v85, v127, v127, v85
	v_lshlrev_b32_e32 v128, 16, v74
	v_lshlrev_b32_e32 v132, 16, v72
	v_lshlrev_b32_e32 v130, 16, v75
	v_lshlrev_b32_e32 v134, 16, v73
	v_mul_f32_e32 v88, v133, v133
	v_mul_f32_e32 v89, v129, v129
	v_and_b32_e32 v131, 0xffff0000, v75
	v_and_b32_e32 v135, 0xffff0000, v73
	v_fma_f32 v86, v132, v132, v88
	v_fma_f32 v87, v128, v128, v89
	v_fma_f32 v86, v134, v134, v86
	v_fma_f32 v87, v130, v130, v87
	v_add_f32_e32 v84, v84, v85
	v_fma_f32 v86, v135, v135, v86
	v_fma_f32 v87, v131, v131, v87
	v_add_f32_e32 v84, v87, v84
	v_add_f32_e32 v84, v86, v84
	ds_bpermute_b32 v85, v249, v84
	s_add_i32 s2, s56, 0xffff8000
	s_waitcnt lgkmcnt(0)
	v_add_f32_e32 v84, v84, v85
	ds_bpermute_b32 v85, v248, v84
	s_ashr_i32 s3, s56, 31
	s_mov_b32 s60, s83
	s_waitcnt lgkmcnt(0)
	v_add_f32_e32 v84, v84, v85
	s_nop 1
	v_mov_b32_dpp v85, v84 row_ror:8 row_mask:0xf bank_mask:0xf
	s_cmpk_gt_i32 s56, 0x7fff
	s_mov_b32 s61, s84
	s_waitcnt lgkmcnt(0)
	v_add_f32_e32 v84, v84, v85
	s_nop 1
	v_mov_b32_dpp v85, v84 row_half_mirror row_mask:0xf bank_mask:0xf
	s_nop 1
	v_mov_b32_dpp v85, v85 quad_perm:[3,2,1,0] row_mask:0xf bank_mask:0xf
	s_mov_b32 s18, s85
	s_cselect_b32 s3, 0, s3
	s_waitcnt lgkmcnt(0)
	v_add_f32_e32 v84, v84, v85
	s_nop 1
	v_mov_b32_dpp v85, v84 quad_perm:[2,3,0,1] row_mask:0xf bank_mask:0xf
	s_cselect_b32 s2, s2, s56
	s_cselect_b32 s19, s18, s61
	s_waitcnt lgkmcnt(0)
	v_add_f32_e32 v104, v84, v85
	s_nop 1
	v_mov_b32_dpp v105, v104 quad_perm:[1,0,3,2] row_mask:0xf bank_mask:0xf
	s_mov_b32 s18, s86
	s_cselect_b32 s18, s18, s60
	s_lshl_b64 s[2:3], s[2:3], 12
	s_add_u32 s18, s18, s2
	s_addc_u32 s19, s19, s3
	s_and_b32 s2, s1, 0xfffff000
	s_waitcnt lgkmcnt(0)
	v_add_f32_e32 v104, v104, v105
	v_add_u32_e32 v103, s2, v100
	v_fmamk_f32 v104, v104, 0x3a800000, v218
	s_mov_b32 s2, 0x800000
	v_mul_f32_e32 v105, 0x4b800000, v104
	v_cmp_gt_f32_e32 vcc, s2, v104
	ds_read_b128 v[84:87], v100 offset:32768
	ds_read_b128 v[88:91], v100 offset:33792
	ds_read_b128 v[92:95], v103 offset:40960
	ds_read_b128 v[96:99], v103 offset:41984
	v_cndmask_b32_e32 v104, v104, v105, vcc
	v_rsq_f32_e32 v136, v104
	ds_read_b128 v[104:107], v100 offset:34816
	ds_read_b128 v[108:111], v100 offset:35840
	ds_read_b128 v[112:115], v103 offset:43008
	ds_read_b128 v[116:119], v103 offset:44032
	s_mov_b32 s62, s87
	s_mov_b32 s63, s88
	v_mul_f32_e32 v103, 0x45800000, v136
	v_cndmask_b32_e32 v136, v136, v103, vcc
	v_pk_mul_f32 v[120:121], v[136:137], v[120:121] op_sel_hi:[0,1]
	s_waitcnt lgkmcnt(7)
	v_pk_mul_f32 v[84:85], v[84:85], v[120:121]
	s_waitcnt lgkmcnt(5)
	v_pk_fma_f32 v[18:19], v[92:93], v[84:85], v[18:19]
	v_pk_mul_f32 v[84:85], v[136:137], v[122:123] op_sel_hi:[0,1]
	v_pk_mul_f32 v[84:85], v[86:87], v[84:85]
	s_nop 0
	v_pk_fma_f32 v[20:21], v[94:95], v[84:85], v[20:21]
	v_pk_mul_f32 v[84:85], v[136:137], v[124:125] op_sel_hi:[0,1]
	v_pk_mul_f32 v[84:85], v[88:89], v[84:85]
	global_store_dwordx4 v8, v[18:21], s[18:19] nt
	s_waitcnt lgkmcnt(4)
	v_pk_fma_f32 v[22:23], v[96:97], v[84:85], v[22:23]
	v_pk_mul_f32 v[84:85], v[136:137], v[126:127] op_sel_hi:[0,1]
	v_pk_mul_f32 v[84:85], v[90:91], v[84:85]
	s_nop 0
	v_pk_fma_f32 v[24:25], v[98:99], v[84:85], v[24:25]
	v_pk_mul_f32 v[84:85], v[136:137], v[128:129] op_sel_hi:[0,1]
	s_waitcnt lgkmcnt(3)
	v_pk_mul_f32 v[84:85], v[104:105], v[84:85]
	global_store_dwordx4 v8, v[22:25], s[18:19] offset:1024 nt
	s_waitcnt lgkmcnt(1)
	v_pk_fma_f32 v[26:27], v[112:113], v[84:85], v[26:27]
	v_pk_mul_f32 v[84:85], v[136:137], v[130:131] op_sel_hi:[0,1]
	v_pk_mul_f32 v[84:85], v[106:107], v[84:85]
	s_nop 0
	v_pk_fma_f32 v[28:29], v[114:115], v[84:85], v[28:29]
	v_pk_mul_f32 v[84:85], v[136:137], v[132:133] op_sel_hi:[0,1]
	v_pk_mul_f32 v[84:85], v[84:85], v[108:109]
	global_store_dwordx4 v8, v[26:29], s[18:19] offset:2048 nt
	s_waitcnt lgkmcnt(0)
	v_pk_fma_f32 v[30:31], v[116:117], v[84:85], v[30:31]
	v_pk_mul_f32 v[84:85], v[136:137], v[134:135] op_sel_hi:[0,1]
	v_pk_mul_f32 v[84:85], v[84:85], v[110:111]
	s_nop 0
	v_pk_fma_f32 v[32:33], v[118:119], v[84:85], v[32:33]
	global_store_dwordx4 v8, v[30:33], s[18:19] offset:3072 nt
	s_and_b64 vcc, exec, s[48:49]
	s_cbranch_vccnz .LBB0_481
.LBB0_487:
	s_waitcnt vmcnt(10)
	v_mul_f32_e32 v86, v23, v23
	v_mul_f32_e32 v87, v19, v19
	s_waitcnt vmcnt(8)
	v_fma_f32 v84, v22, v22, v86
	v_fma_f32 v85, v18, v18, v87
	v_fma_f32 v84, v24, v24, v84
	v_fma_f32 v85, v20, v20, v85
	v_fma_f32 v84, v25, v25, v84
	v_fma_f32 v85, v21, v21, v85
	v_mul_f32_e32 v88, v31, v31
	v_mul_f32_e32 v89, v27, v27
	v_add_f32_e32 v84, v84, v85
	v_fma_f32 v86, v30, v30, v88
	v_fma_f32 v87, v26, v26, v89
	v_fma_f32 v86, v32, v32, v86
	v_fma_f32 v87, v28, v28, v87
	v_fma_f32 v86, v33, v33, v86
	v_fma_f32 v87, v29, v29, v87
	v_add_f32_e32 v84, v87, v84
	v_add_f32_e32 v84, v86, v84
	s_mov_b32 s2, 0x800000
	s_and_b32 s1, s1, 0xfffff000
	ds_bpermute_b32 v86, v249, v84
	v_add_u32_e32 v98, s1, v101
	ds_read_b128 v[94:97], v98
	v_add_u32_e32 v93, s1, v102
	ds_read_b128 v[110:113], v93
	s_waitcnt lgkmcnt(2)
	v_add_f32_e32 v84, v84, v86
	s_ashr_i32 s57, s56, 31
	ds_read_b128 v[114:117], v100
	ds_bpermute_b32 v86, v248, v84
	s_waitcnt lgkmcnt(0)
	v_add_f32_e32 v84, v84, v86
	s_nop 1
	s_nop 1
	v_mov_b32_dpp v86, v84 row_ror:8 row_mask:0xf bank_mask:0xf
	s_waitcnt lgkmcnt(0)
	v_add_f32_e32 v84, v84, v86
	s_nop 1
	s_nop 1
	v_mov_b32_dpp v86, v84 row_half_mirror row_mask:0xf bank_mask:0xf
	s_nop 1
	v_mov_b32_dpp v86, v86 quad_perm:[3,2,1,0] row_mask:0xf bank_mask:0xf
	s_waitcnt lgkmcnt(0)
	v_add_f32_e32 v84, v84, v86
	s_nop 1
	s_nop 1
	v_mov_b32_dpp v86, v84 quad_perm:[2,3,0,1] row_mask:0xf bank_mask:0xf
	s_waitcnt lgkmcnt(0)
	v_add_f32_e32 v84, v84, v86
	s_nop 1
	s_nop 1
	v_mov_b32_dpp v85, v84 quad_perm:[1,0,3,2] row_mask:0xf bank_mask:0xf
	ds_read_b128 v[86:89], v100 offset:36864
	s_waitcnt lgkmcnt(1)
	v_add_f32_e32 v84, v84, v85
	v_fmamk_f32 v84, v84, 0x3a800000, v218
	v_cmp_gt_f32_e32 vcc, s2, v84
	v_mul_f32_e32 v85, 0x4b800000, v84
	s_lshl_b64 s[2:3], s[56:57], 11
	v_cndmask_b32_e32 v84, v84, v85, vcc
	v_rsq_f32_e32 v84, v84
	s_nop 0
	v_mul_f32_e32 v85, 0x45800000, v84
	v_cndmask_b32_e32 v92, v84, v85, vcc
	v_pk_mul_f32 v[84:85], v[18:19], v[92:93] op_sel_hi:[1,0]
	v_pk_mul_f32 v[118:119], v[22:23], v[92:93] op_sel_hi:[1,0]
	s_waitcnt lgkmcnt(0)
	v_pk_mul_f32 v[84:85], v[86:87], v[84:85]
	v_pk_add_f32 v[86:87], v[94:95], 1.0 op_sel_hi:[1,0]
	s_nop 0
	v_pk_fma_f32 v[86:87], v[86:87], v[84:85], v[110:111]
	v_pk_mul_f32 v[84:85], v[20:21], v[92:93] op_sel_hi:[1,0]
	v_mul_f32_e32 v94, v115, v87
	v_pk_mul_f32 v[84:85], v[88:89], v[84:85]
	v_pk_add_f32 v[88:89], v[96:97], 1.0 op_sel_hi:[1,0]
	v_fmac_f32_e32 v94, v114, v86
	v_pk_fma_f32 v[84:85], v[88:89], v[84:85], v[112:113]
	ds_read_b128 v[88:91], v100 offset:4096
	v_fmac_f32_e32 v94, v116, v84
	v_fmac_f32_e32 v94, v117, v85
	v_add_f32_e32 v109, 0, v94
	ds_read_b128 v[94:97], v100 offset:8192
	s_waitcnt lgkmcnt(1)
	v_mul_f32_e32 v89, v89, v87
	v_fmac_f32_e32 v89, v88, v86
	v_fmac_f32_e32 v89, v90, v84
	v_fmac_f32_e32 v89, v91, v85
	v_add_f32_e32 v122, 0, v89
	ds_read_b128 v[88:91], v100 offset:12288
	s_waitcnt lgkmcnt(1)
	v_mul_f32_e32 v95, v95, v87
	v_fmac_f32_e32 v95, v94, v86
	v_fmac_f32_e32 v95, v96, v84
	v_fmac_f32_e32 v95, v97, v85
	v_add_f32_e32 v123, 0, v95
	ds_read_b128 v[94:97], v100 offset:16384
	s_waitcnt lgkmcnt(1)
	v_mul_f32_e32 v89, v89, v87
	v_fmac_f32_e32 v89, v88, v86
	v_fmac_f32_e32 v89, v90, v84
	v_fmac_f32_e32 v89, v91, v85
	v_add_f32_e32 v99, 0, v89
	ds_read_b128 v[88:91], v100 offset:20480
	ds_read_b128 v[110:113], v100 offset:24576
	s_waitcnt lgkmcnt(2)
	v_mul_f32_e32 v95, v95, v87
	v_fmac_f32_e32 v95, v94, v86
	v_fmac_f32_e32 v95, v96, v84
	s_waitcnt lgkmcnt(1)
	v_mul_f32_e32 v89, v89, v87
	v_fmac_f32_e32 v89, v88, v86
	v_fmac_f32_e32 v89, v90, v84
	v_fmac_f32_e32 v95, v97, v85
	v_fmac_f32_e32 v89, v91, v85
	v_add_f32_e32 v96, 0, v95
	v_add_f32_e32 v95, 0, v89
	ds_read_b128 v[88:91], v100 offset:28672
	s_waitcnt lgkmcnt(1)
	v_mul_f32_e32 v94, v111, v87
	v_fmac_f32_e32 v94, v110, v86
	v_fmac_f32_e32 v94, v112, v84
	v_fmac_f32_e32 v94, v113, v85
	s_waitcnt lgkmcnt(0)
	v_mul_f32_e32 v97, v87, v89
	v_fmac_f32_e32 v97, v86, v88
	v_fmac_f32_e32 v97, v84, v90
	v_fmac_f32_e32 v97, v85, v91
	ds_read_b128 v[88:91], v100 offset:37888
	ds_read_b128 v[110:113], v98 offset:1024
	ds_read_b128 v[114:117], v93 offset:1024
	v_add_f32_e32 v94, 0, v94
	v_add_f32_e32 v97, 0, v97
	s_waitcnt lgkmcnt(2)
	v_pk_mul_f32 v[88:89], v[118:119], v[88:89]
	ds_read_b128 v[118:121], v100 offset:1024
	s_waitcnt lgkmcnt(2)
	v_pk_add_f32 v[110:111], v[110:111], 1.0 op_sel_hi:[1,0]
	v_cvt_pk_bf16_f32 v86, v86, v87
	s_waitcnt lgkmcnt(1)
	v_pk_fma_f32 v[88:89], v[88:89], v[110:111], v[114:115]
	v_pk_mul_f32 v[110:111], v[24:25], v[92:93] op_sel_hi:[1,0]
	s_nop 0
	v_pk_mul_f32 v[90:91], v[110:111], v[90:91]
	v_pk_add_f32 v[110:111], v[112:113], 1.0 op_sel_hi:[1,0]
	s_nop 0
	v_pk_fma_f32 v[90:91], v[90:91], v[110:111], v[116:117]
	ds_read_b128 v[110:113], v100 offset:5120
	s_waitcnt lgkmcnt(1)
	v_mul_f32_e32 v114, v89, v119
	v_fmac_f32_e32 v114, v88, v118
	v_fmac_f32_e32 v114, v90, v120
	v_fmac_f32_e32 v114, v91, v121
	v_add_f32_e32 v109, v109, v114
	ds_read_b128 v[114:117], v100 offset:9216
	s_waitcnt lgkmcnt(1)
	v_mul_f32_e32 v111, v89, v111
	v_fmac_f32_e32 v111, v88, v110
	v_fmac_f32_e32 v111, v90, v112
	v_fmac_f32_e32 v111, v91, v113
	v_add_f32_e32 v126, v122, v111
	ds_read_b128 v[110:113], v100 offset:13312
	s_waitcnt lgkmcnt(1)
	v_mul_f32_e32 v115, v89, v115
	v_fmac_f32_e32 v115, v88, v114
	v_fmac_f32_e32 v115, v90, v116
	v_fmac_f32_e32 v115, v91, v117
	v_add_f32_e32 v127, v123, v115
	ds_read_b128 v[114:117], v100 offset:17408
	s_waitcnt lgkmcnt(1)
	v_mul_f32_e32 v111, v89, v111
	v_fmac_f32_e32 v111, v88, v110
	v_fmac_f32_e32 v111, v90, v112
	v_fmac_f32_e32 v111, v91, v113
	v_add_f32_e32 v99, v99, v111
	ds_read_b128 v[110:113], v100 offset:21504
	s_waitcnt lgkmcnt(1)
	v_mul_f32_e32 v115, v89, v115
	v_fmac_f32_e32 v115, v88, v114
	v_fmac_f32_e32 v115, v90, v116
	v_fmac_f32_e32 v115, v91, v117
	v_add_f32_e32 v128, v96, v115
	ds_read_b128 v[114:117], v100 offset:25600
	s_waitcnt lgkmcnt(1)
	v_mul_f32_e32 v96, v89, v111
	v_fmac_f32_e32 v96, v88, v110
	v_fmac_f32_e32 v96, v90, v112
	v_fmac_f32_e32 v96, v91, v113
	ds_read_b128 v[110:113], v100 offset:29696
	v_add_f32_e32 v129, v95, v96
	s_waitcnt lgkmcnt(1)
	v_mul_f32_e32 v95, v89, v115
	v_fmac_f32_e32 v95, v88, v114
	v_fmac_f32_e32 v95, v90, v116
	v_fmac_f32_e32 v95, v91, v117
	v_add_f32_e32 v130, v94, v95
	s_waitcnt lgkmcnt(0)
	v_mul_f32_e32 v94, v89, v111
	v_fmac_f32_e32 v94, v88, v110
	v_fmac_f32_e32 v94, v90, v112
	v_fmac_f32_e32 v94, v91, v113
	ds_read_b128 v[110:113], v100 offset:38912
	ds_read_b128 v[114:117], v98 offset:2048
	ds_read_b128 v[118:121], v93 offset:2048
	ds_read_b128 v[122:125], v100 offset:2048
	v_add_f32_e32 v131, v97, v94
	v_pk_mul_f32 v[94:95], v[26:27], v[92:93] op_sel_hi:[1,0]
	s_waitcnt lgkmcnt(2)
	v_pk_add_f32 v[96:97], v[114:115], 1.0 op_sel_hi:[1,0]
	v_pk_mul_f32 v[94:95], v[94:95], v[110:111]
	v_pk_add_f32 v[110:111], v[116:117], 1.0 op_sel_hi:[1,0]
	s_waitcnt lgkmcnt(1)
	v_pk_fma_f32 v[94:95], v[94:95], v[96:97], v[118:119]
	v_pk_mul_f32 v[96:97], v[28:29], v[92:93] op_sel_hi:[1,0]
	s_nop 0
	v_pk_mul_f32 v[96:97], v[96:97], v[112:113]
	s_nop 0
	v_pk_fma_f32 v[96:97], v[96:97], v[110:111], v[120:121]
	ds_read_b128 v[110:113], v100 offset:6144
	s_waitcnt lgkmcnt(1)
	v_mul_f32_e32 v114, v95, v123
	v_fmac_f32_e32 v114, v94, v122
	v_fmac_f32_e32 v114, v96, v124
	v_fmac_f32_e32 v114, v97, v125
	v_add_f32_e32 v132, v109, v114
	ds_read_b128 v[114:117], v100 offset:10240
	s_waitcnt lgkmcnt(1)
	v_mul_f32_e32 v109, v95, v111
	v_fmac_f32_e32 v109, v94, v110
	v_fmac_f32_e32 v109, v96, v112
	v_fmac_f32_e32 v109, v97, v113
	ds_read_b128 v[110:113], v100 offset:14336
	v_add_f32_e32 v133, v126, v109
	s_waitcnt lgkmcnt(1)
	v_mul_f32_e32 v109, v95, v115
	v_fmac_f32_e32 v109, v94, v114
	v_fmac_f32_e32 v109, v96, v116
	v_fmac_f32_e32 v109, v97, v117
	ds_read_b128 v[114:117], v100 offset:18432
	ds_read_b128 v[118:121], v100 offset:22528
	v_add_f32_e32 v134, v127, v109
	s_waitcnt lgkmcnt(2)
	v_mul_f32_e32 v109, v95, v111
	v_fmac_f32_e32 v109, v94, v110
	v_fmac_f32_e32 v109, v96, v112
	v_fmac_f32_e32 v109, v97, v113
	v_add_f32_e32 v113, v99, v109
	s_waitcnt lgkmcnt(1)
	v_mul_f32_e32 v99, v95, v115
	v_fmac_f32_e32 v99, v94, v114
	v_fmac_f32_e32 v99, v96, v116
	v_fmac_f32_e32 v99, v97, v117
	ds_read_b128 v[114:117], v100 offset:26624
	v_add_f32_e32 v111, v128, v99
	s_waitcnt lgkmcnt(1)
	v_mul_f32_e32 v99, v95, v119
	v_fmac_f32_e32 v99, v94, v118
	v_fmac_f32_e32 v99, v96, v120
	v_fmac_f32_e32 v99, v97, v121
	ds_read_b128 v[118:121], v100 offset:30720
	v_add_f32_e32 v110, v129, v99
	s_waitcnt lgkmcnt(1)
	v_mul_f32_e32 v99, v95, v115
	v_fmac_f32_e32 v99, v94, v114
	v_fmac_f32_e32 v99, v96, v116
	v_fmac_f32_e32 v99, v97, v117
	v_add_f32_e32 v109, v130, v99
	s_waitcnt lgkmcnt(0)
	v_mul_f32_e32 v99, v95, v119
	v_fmac_f32_e32 v99, v94, v118
	v_fmac_f32_e32 v99, v96, v120
	v_fmac_f32_e32 v99, v97, v121
	ds_read_b128 v[114:117], v100 offset:39936
	ds_read_b128 v[118:121], v98 offset:3072
	ds_read_b128 v[122:125], v93 offset:3072
	v_add_f32_e32 v112, v131, v99
	v_pk_mul_f32 v[98:99], v[30:31], v[92:93] op_sel_hi:[1,0]
	v_pk_mul_f32 v[92:93], v[32:33], v[92:93] op_sel_hi:[1,0]
	s_waitcnt lgkmcnt(2)
	v_pk_mul_f32 v[98:99], v[98:99], v[114:115]
	s_waitcnt lgkmcnt(1)
	v_pk_add_f32 v[114:115], v[118:119], 1.0 op_sel_hi:[1,0]
	v_pk_mul_f32 v[92:93], v[92:93], v[116:117]
	s_waitcnt lgkmcnt(0)
	v_pk_fma_f32 v[98:99], v[98:99], v[114:115], v[122:123]
	v_pk_add_f32 v[114:115], v[120:121], 1.0 op_sel_hi:[1,0]
	ds_read_b128 v[126:129], v100 offset:3072
	v_pk_fma_f32 v[92:93], v[92:93], v[114:115], v[124:125]
	ds_read_b128 v[114:117], v100 offset:7168
	s_waitcnt lgkmcnt(1)
	v_mul_f32_e32 v118, v99, v127
	v_fmac_f32_e32 v118, v98, v126
	s_waitcnt lgkmcnt(0)
	v_mul_f32_e32 v115, v99, v115
	v_fmac_f32_e32 v115, v98, v114
	v_fmac_f32_e32 v118, v92, v128
	v_fmac_f32_e32 v115, v92, v116
	v_fmac_f32_e32 v118, v93, v129
	v_fmac_f32_e32 v115, v93, v117
	v_add_f32_e32 v122, v132, v118
	ds_read_b128 v[118:121], v100 offset:11264
	v_add_f32_e32 v123, v133, v115
	ds_read_b128 v[114:117], v100 offset:15360
	s_waitcnt lgkmcnt(1)
	v_mul_f32_e32 v119, v99, v119
	v_fmac_f32_e32 v119, v98, v118
	s_waitcnt lgkmcnt(0)
	v_mul_f32_e32 v115, v99, v115
	v_fmac_f32_e32 v115, v98, v114
	v_fmac_f32_e32 v119, v92, v120
	v_fmac_f32_e32 v115, v92, v116
	v_fmac_f32_e32 v119, v93, v121
	v_fmac_f32_e32 v115, v93, v117
	v_add_f32_e32 v124, v134, v119
	ds_read_b128 v[118:121], v100 offset:19456
	v_add_f32_e32 v113, v113, v115
	ds_read_b128 v[114:117], v100 offset:23552
	s_waitcnt lgkmcnt(1)
	v_mul_f32_e32 v119, v99, v119
	v_fmac_f32_e32 v119, v98, v118
	s_waitcnt lgkmcnt(0)
	v_mul_f32_e32 v115, v99, v115
	v_fmac_f32_e32 v115, v98, v114
	v_fmac_f32_e32 v119, v92, v120
	v_fmac_f32_e32 v115, v92, v116
	v_fmac_f32_e32 v119, v93, v121
	v_fmac_f32_e32 v115, v93, v117
	v_add_f32_e32 v111, v111, v119
	ds_read_b128 v[118:121], v100 offset:27648
	v_add_f32_e32 v110, v110, v115
	ds_read_b128 v[114:117], v100 offset:31744
	s_waitcnt lgkmcnt(1)
	v_mul_f32_e32 v119, v99, v119
	v_fmac_f32_e32 v119, v98, v118
	s_waitcnt lgkmcnt(0)
	v_mul_f32_e32 v115, v99, v115
	v_fmac_f32_e32 v115, v98, v114
	v_cndmask_b32_e64 v114, v122, v111, s[40:41]
	ds_bpermute_b32 v114, v249, v114
	v_fmac_f32_e32 v119, v92, v120
	v_fmac_f32_e32 v115, v92, v116
	v_fmac_f32_e32 v119, v93, v121
	v_fmac_f32_e32 v115, v93, v117
	v_add_f32_e32 v109, v109, v119
	v_add_f32_e32 v112, v112, v115
	v_cndmask_b32_e64 v111, v111, v122, s[40:41]
	s_waitcnt lgkmcnt(0)
	v_add_f32_e32 v111, v111, v114
	v_cndmask_b32_e64 v114, v110, v123, s[40:41]
	v_cndmask_b32_e64 v110, v123, v110, s[40:41]
	v_cndmask_b32_e64 v115, v124, v109, s[40:41]
	v_cndmask_b32_e64 v116, v113, v112, s[40:41]
	ds_bpermute_b32 v110, v249, v110
	ds_bpermute_b32 v115, v249, v115
	ds_bpermute_b32 v108, v249, v116
	v_cndmask_b32_e64 v109, v109, v124, s[40:41]
	v_cndmask_b32_e64 v112, v112, v113, s[40:41]
	s_waitcnt lgkmcnt(2)
	v_add_f32_e32 v110, v114, v110
	s_waitcnt lgkmcnt(1)
	v_add_f32_e32 v109, v109, v115
	s_waitcnt lgkmcnt(0)
	v_add_f32_e32 v108, v112, v108
	v_cndmask_b32_e64 v112, v111, v109, s[42:43]
	v_cndmask_b32_e64 v113, v110, v108, s[42:43]
	ds_bpermute_b32 v112, v248, v112
	ds_bpermute_b32 v107, v248, v113
	v_cndmask_b32_e64 v109, v109, v111, s[42:43]
	v_cndmask_b32_e64 v108, v108, v110, s[42:43]
	s_waitcnt lgkmcnt(1)
	v_add_f32_e32 v109, v109, v112
	s_waitcnt lgkmcnt(0)
	v_add_f32_e32 v107, v108, v107
	v_cndmask_b32_e64 v108, v109, v107, s[44:45]
	s_nop 1
	v_mov_b32_dpp v106, v108 row_ror:8 row_mask:0xf bank_mask:0xf
	v_cndmask_b32_e64 v87, v107, v109, s[44:45]
	s_waitcnt lgkmcnt(0)
	v_add_f32_e32 v108, v87, v106
	s_nop 1
	v_mov_b32_dpp v105, v108 row_half_mirror row_mask:0xf bank_mask:0xf
	s_nop 1
	v_mov_b32_dpp v105, v105 quad_perm:[3,2,1,0] row_mask:0xf bank_mask:0xf
	v_cvt_pk_bf16_f32 v87, v84, v85
	v_cvt_pk_bf16_f32 v84, v88, v89
	v_lshl_add_u64 v[106:107], v[66:67], 0, s[2:3]
	v_cvt_pk_bf16_f32 v85, v90, v91
	s_waitcnt lgkmcnt(0)
	v_add_f32_e32 v88, v108, v105
	s_nop 1
	v_mov_b32_dpp v89, v88 quad_perm:[2,3,0,1] row_mask:0xf bank_mask:0xf
	global_store_dwordx2 v[106:107], v[84:85], off offset:512
	global_store_dwordx2 v[106:107], v[86:87], off
	v_cvt_pk_bf16_f32 v86, v94, v95
	v_cvt_pk_bf16_f32 v87, v96, v97
	s_waitcnt lgkmcnt(0)
	v_add_f32_e32 v84, v88, v89
	ds_bpermute_b32 v85, v244, v84
	global_store_dwordx2 v[106:107], v[86:87], off offset:1024
	v_cvt_pk_bf16_f32 v86, v98, v99
	v_cvt_pk_bf16_f32 v87, v92, v93
	global_store_dwordx2 v[106:107], v[86:87], off offset:1536
	s_and_saveexec_b64 s[18:19], s[46:47]
	s_cbranch_execz .LBB0_489
	s_lshl_b64 s[2:3], s[56:57], 5
	s_waitcnt lgkmcnt(0)
	v_add_f32_e32 v86, v84, v85
	v_lshl_add_u64 v[84:85], v[64:65], 0, s[2:3]
	global_store_dword v[84:85], v86, off

.LBB0_504:
	s_waitcnt vmcnt(6)
	v_lshlrev_b32_e32 v116, 16, v76
	v_and_b32_e32 v117, 0xffff0000, v76
	v_and_b32_e32 v113, 0xffff0000, v78
	v_lshlrev_b32_e32 v112, 16, v78
	v_lshlrev_b32_e32 v114, 16, v79
	v_and_b32_e32 v115, 0xffff0000, v79
	v_lshlrev_b32_e32 v118, 16, v77
	v_and_b32_e32 v119, 0xffff0000, v77
	v_mul_f32_e32 v78, v113, v113
	v_mul_f32_e32 v79, v117, v117
	s_waitcnt vmcnt(5)
	v_and_b32_e32 v121, 0xffff0000, v82
	v_fma_f32 v76, v112, v112, v78
	v_fma_f32 v77, v116, v116, v79
	s_waitcnt vmcnt(4)
	v_lshlrev_b32_e32 v124, 16, v80
	v_and_b32_e32 v125, 0xffff0000, v80
	v_lshlrev_b32_e32 v126, 16, v81
	v_and_b32_e32 v127, 0xffff0000, v81
	v_fma_f32 v76, v114, v114, v76
	v_fma_f32 v77, v118, v118, v77
	v_lshlrev_b32_e32 v120, 16, v82
	v_fma_f32 v76, v115, v115, v76
	v_fma_f32 v77, v119, v119, v77
	v_lshlrev_b32_e32 v122, 16, v83
	v_mul_f32_e32 v80, v121, v121
	v_mul_f32_e32 v81, v125, v125
	v_and_b32_e32 v123, 0xffff0000, v83
	v_fma_f32 v78, v120, v120, v80
	v_fma_f32 v79, v124, v124, v81
	v_fma_f32 v78, v122, v122, v78
	v_fma_f32 v79, v126, v126, v79
	v_add_f32_e32 v76, v76, v77
	v_fma_f32 v78, v123, v123, v78
	v_fma_f32 v79, v127, v127, v79
	v_add_f32_e32 v76, v76, v78
	v_add_f32_e32 v76, v76, v79
	ds_bpermute_b32 v77, v249, v76
	s_add_i32 s2, s52, 0xffff8000
	s_waitcnt lgkmcnt(0)
	v_add_f32_e32 v76, v76, v77
	ds_bpermute_b32 v77, v248, v76
	s_ashr_i32 s3, s52, 31
	s_mov_b32 s60, s83
	s_waitcnt lgkmcnt(0)
	v_add_f32_e32 v76, v76, v77
	s_nop 1
	v_mov_b32_dpp v77, v76 row_ror:8 row_mask:0xf bank_mask:0xf
	s_cmpk_gt_i32 s52, 0x7fff
	s_mov_b32 s61, s84
	s_waitcnt lgkmcnt(0)
	v_add_f32_e32 v76, v76, v77
	s_nop 1
	v_mov_b32_dpp v77, v76 row_half_mirror row_mask:0xf bank_mask:0xf
	s_nop 1
	v_mov_b32_dpp v77, v77 quad_perm:[3,2,1,0] row_mask:0xf bank_mask:0xf
	s_mov_b32 s18, s85
	s_cselect_b32 s3, 0, s3
	s_waitcnt lgkmcnt(0)
	v_add_f32_e32 v76, v76, v77
	s_nop 1
	v_mov_b32_dpp v77, v76 quad_perm:[2,3,0,1] row_mask:0xf bank_mask:0xf
	s_cselect_b32 s2, s2, s52
	s_cselect_b32 s19, s18, s61
	s_waitcnt lgkmcnt(0)
	v_add_f32_e32 v92, v76, v77
	s_nop 1
	v_mov_b32_dpp v93, v92 quad_perm:[1,0,3,2] row_mask:0xf bank_mask:0xf
	s_mov_b32 s18, s86
	s_cselect_b32 s18, s18, s60
	s_lshl_b64 s[2:3], s[2:3], 12
	s_add_u32 s18, s18, s2
	s_addc_u32 s19, s19, s3
	s_and_b32 s2, s1, 0xfffff000
	s_waitcnt lgkmcnt(0)
	v_add_f32_e32 v92, v92, v93
	v_add_u32_e32 v103, s2, v100
	v_fmamk_f32 v92, v92, 0x3a800000, v218
	s_mov_b32 s2, 0x800000
	v_mul_f32_e32 v93, 0x4b800000, v92
	v_cmp_gt_f32_e32 vcc, s2, v92
	ds_read_b128 v[76:79], v100 offset:32768
	ds_read_b128 v[80:83], v100 offset:33792
	ds_read_b128 v[84:87], v103 offset:40960
	ds_read_b128 v[88:91], v103 offset:41984
	v_cndmask_b32_e32 v92, v92, v93, vcc
	v_rsq_f32_e32 v128, v92
	ds_read_b128 v[92:95], v100 offset:34816
	ds_read_b128 v[96:99], v100 offset:35840
	ds_read_b128 v[104:107], v103 offset:43008
	ds_read_b128 v[108:111], v103 offset:44032
	s_mov_b32 s62, s87
	s_mov_b32 s63, s88
	v_mul_f32_e32 v103, 0x45800000, v128
	v_cndmask_b32_e32 v128, v128, v103, vcc
	v_pk_mul_f32 v[112:113], v[128:129], v[112:113] op_sel_hi:[0,1]
	s_waitcnt lgkmcnt(7)
	v_pk_mul_f32 v[76:77], v[76:77], v[112:113]
	s_waitcnt lgkmcnt(5)
	v_pk_fma_f32 v[46:47], v[84:85], v[76:77], v[46:47]
	v_pk_mul_f32 v[76:77], v[128:129], v[114:115] op_sel_hi:[0,1]
	v_pk_mul_f32 v[76:77], v[78:79], v[76:77]
	s_nop 0
	v_pk_fma_f32 v[48:49], v[86:87], v[76:77], v[48:49]
	v_pk_mul_f32 v[76:77], v[128:129], v[116:117] op_sel_hi:[0,1]
	v_pk_mul_f32 v[76:77], v[80:81], v[76:77]
	global_store_dwordx4 v8, v[46:49], s[18:19] nt
	s_waitcnt lgkmcnt(4)
	v_pk_fma_f32 v[42:43], v[88:89], v[76:77], v[42:43]
	v_pk_mul_f32 v[76:77], v[128:129], v[118:119] op_sel_hi:[0,1]
	v_pk_mul_f32 v[76:77], v[82:83], v[76:77]
	s_nop 0
	v_pk_fma_f32 v[44:45], v[90:91], v[76:77], v[44:45]
	v_pk_mul_f32 v[76:77], v[128:129], v[120:121] op_sel_hi:[0,1]
	s_waitcnt lgkmcnt(3)
	v_pk_mul_f32 v[76:77], v[92:93], v[76:77]
	global_store_dwordx4 v8, v[42:45], s[18:19] offset:1024 nt
	s_waitcnt lgkmcnt(1)
	v_pk_fma_f32 v[38:39], v[104:105], v[76:77], v[38:39]
	v_pk_mul_f32 v[76:77], v[128:129], v[122:123] op_sel_hi:[0,1]
	v_pk_mul_f32 v[76:77], v[94:95], v[76:77]
	s_nop 0
	v_pk_fma_f32 v[40:41], v[106:107], v[76:77], v[40:41]
	v_pk_mul_f32 v[76:77], v[128:129], v[124:125] op_sel_hi:[0,1]
	v_pk_mul_f32 v[76:77], v[76:77], v[96:97]
	global_store_dwordx4 v8, v[38:41], s[18:19] offset:2048 nt
	s_waitcnt lgkmcnt(0)
	v_pk_fma_f32 v[34:35], v[108:109], v[76:77], v[34:35]
	v_pk_mul_f32 v[76:77], v[128:129], v[126:127] op_sel_hi:[0,1]
	v_pk_mul_f32 v[76:77], v[76:77], v[98:99]
	s_nop 0
	v_pk_fma_f32 v[36:37], v[110:111], v[76:77], v[36:37]
	global_store_dwordx4 v8, v[34:37], s[18:19] offset:3072 nt
	s_and_b64 vcc, exec, s[48:49]
	s_cbranch_vccnz .LBB0_451
.LBB0_505:
	s_waitcnt vmcnt(6)
	v_mul_f32_e32 v78, v43, v43
	v_mul_f32_e32 v79, v47, v47
	s_waitcnt vmcnt(4)
	v_fma_f32 v76, v42, v42, v78
	v_fma_f32 v77, v46, v46, v79
	v_fma_f32 v76, v44, v44, v76
	v_fma_f32 v77, v48, v48, v77
	v_fma_f32 v76, v45, v45, v76
	v_fma_f32 v77, v49, v49, v77
	v_mul_f32_e32 v80, v35, v35
	v_mul_f32_e32 v81, v39, v39
	v_add_f32_e32 v76, v76, v77
	v_fma_f32 v78, v34, v34, v80
	v_fma_f32 v79, v38, v38, v81
	v_fma_f32 v78, v36, v36, v78
	v_fma_f32 v79, v40, v40, v79
	v_fma_f32 v78, v37, v37, v78
	v_fma_f32 v79, v41, v41, v79
	v_and_b32_e32 v77, 64, v220
	v_add_f32_e32 v76, v79, v76
	v_add_f32_e32 v76, v78, v76
	v_add_u32_e32 v77, 64, v77
	s_mov_b32 s2, 0x800000
	s_and_b32 s1, s1, 0xfffff000
	ds_bpermute_b32 v78, v249, v76
	v_add_u32_e32 v84, s1, v101
	ds_read_b128 v[86:89], v100 offset:36864
	ds_read_b128 v[90:93], v84
	s_ashr_i32 s53, s52, 31
	s_waitcnt lgkmcnt(2)
	v_add_f32_e32 v76, v76, v78
	s_nop 1
	ds_bpermute_b32 v78, v248, v76
	s_waitcnt lgkmcnt(0)
	v_add_f32_e32 v76, v76, v78
	s_nop 1
	s_nop 1
	v_mov_b32_dpp v78, v76 row_ror:8 row_mask:0xf bank_mask:0xf
	s_waitcnt lgkmcnt(0)
	v_add_f32_e32 v76, v76, v78
	s_nop 1
	s_nop 1
	v_mov_b32_dpp v78, v76 row_half_mirror row_mask:0xf bank_mask:0xf
	s_nop 1
	v_mov_b32_dpp v78, v78 quad_perm:[3,2,1,0] row_mask:0xf bank_mask:0xf
	s_waitcnt lgkmcnt(0)
	v_add_f32_e32 v76, v76, v78
	s_nop 1
	s_nop 1
	v_mov_b32_dpp v83, v76 quad_perm:[2,3,0,1] row_mask:0xf bank_mask:0xf
	s_waitcnt lgkmcnt(0)
	v_add_f32_e32 v76, v76, v83
	v_xor_b32_e32 v83, 1, v220
	v_cmp_lt_i32_e32 vcc, v83, v77
	s_nop 1
	v_cndmask_b32_e32 v77, v220, v83, vcc
	v_lshlrev_b32_e32 v77, 2, v77
	s_nop 1
	v_mov_b32_dpp v83, v76 quad_perm:[1,0,3,2] row_mask:0xf bank_mask:0xf
	s_waitcnt lgkmcnt(0)
	v_add_f32_e32 v76, v76, v83
	v_fmamk_f32 v76, v76, 0x3a800000, v218
	v_cmp_gt_f32_e32 vcc, s2, v76
	v_mul_f32_e32 v83, 0x4b800000, v76
	s_lshl_b64 s[2:3], s[52:53], 11
	v_cndmask_b32_e32 v76, v76, v83, vcc
	v_rsq_f32_e32 v76, v76
	s_nop 0
	v_mul_f32_e32 v83, 0x45800000, v76
	v_cndmask_b32_e32 v76, v76, v83, vcc
	v_add_u32_e32 v83, s1, v102
	ds_read_b128 v[94:97], v83
	v_pk_mul_f32 v[46:47], v[46:47], v[76:77] op_sel_hi:[1,0]
	v_pk_mul_f32 v[42:43], v[42:43], v[76:77] op_sel_hi:[1,0]
	v_pk_mul_f32 v[46:47], v[86:87], v[46:47]
	v_pk_add_f32 v[86:87], v[90:91], 1.0 op_sel_hi:[1,0]
	v_pk_mul_f32 v[44:45], v[44:45], v[76:77] op_sel_hi:[1,0]
	s_waitcnt lgkmcnt(0)
	v_pk_fma_f32 v[94:95], v[86:87], v[46:47], v[94:95]
	v_pk_mul_f32 v[46:47], v[48:49], v[76:77] op_sel_hi:[1,0]
	v_pk_add_f32 v[48:49], v[92:93], 1.0 op_sel_hi:[1,0]
	v_pk_mul_f32 v[46:47], v[88:89], v[46:47]
	ds_read_b128 v[86:89], v100
	v_pk_fma_f32 v[92:93], v[48:49], v[46:47], v[96:97]
	v_cvt_pk_bf16_f32 v48, v94, v95
	v_cvt_pk_bf16_f32 v49, v92, v93
	v_lshl_add_u64 v[46:47], v[66:67], 0, s[2:3]
	global_store_dwordx2 v[46:47], v[48:49], off
	s_waitcnt lgkmcnt(0)
	v_mul_f32_e32 v48, v87, v95
	v_fmac_f32_e32 v48, v86, v94
	v_fmac_f32_e32 v48, v88, v92
	v_fmac_f32_e32 v48, v89, v93
	ds_read_b128 v[86:89], v100 offset:4096
	v_add_f32_e32 v103, 0, v48
	v_pk_mul_f32 v[38:39], v[38:39], v[76:77] op_sel_hi:[1,0]
	v_pk_mul_f32 v[34:35], v[34:35], v[76:77] op_sel_hi:[1,0]
	v_pk_mul_f32 v[36:37], v[36:37], v[76:77] op_sel_hi:[1,0]
	s_waitcnt lgkmcnt(0)
	v_mul_f32_e32 v48, v87, v95
	v_fmac_f32_e32 v48, v86, v94
	v_fmac_f32_e32 v48, v88, v92
	v_fmac_f32_e32 v48, v89, v93
	ds_read_b128 v[86:89], v100 offset:8192
	v_add_f32_e32 v104, 0, v48
	s_waitcnt lgkmcnt(0)
	v_mul_f32_e32 v48, v87, v95
	v_fmac_f32_e32 v48, v86, v94
	v_fmac_f32_e32 v48, v88, v92
	v_fmac_f32_e32 v48, v89, v93
	ds_read_b128 v[86:89], v100 offset:12288
	v_add_f32_e32 v105, 0, v48
	s_waitcnt lgkmcnt(0)
	v_mul_f32_e32 v48, v87, v95
	v_fmac_f32_e32 v48, v86, v94
	v_fmac_f32_e32 v48, v88, v92
	v_fmac_f32_e32 v48, v89, v93
	ds_read_b128 v[88:91], v100 offset:16384
	v_add_f32_e32 v87, 0, v48
	s_waitcnt lgkmcnt(0)
	v_mul_f32_e32 v48, v89, v95
	v_fmac_f32_e32 v48, v88, v94
	v_fmac_f32_e32 v48, v90, v92
	v_fmac_f32_e32 v48, v91, v93
	ds_read_b128 v[88:91], v100 offset:20480
	v_add_f32_e32 v86, 0, v48
	s_waitcnt lgkmcnt(0)
	v_mul_f32_e32 v48, v89, v95
	v_fmac_f32_e32 v48, v88, v94
	v_fmac_f32_e32 v48, v90, v92
	v_fmac_f32_e32 v48, v91, v93
	ds_read_b128 v[88:91], v100 offset:24576
	v_add_f32_e32 v85, 0, v48
	s_waitcnt lgkmcnt(0)
	v_mul_f32_e32 v48, v89, v95
	v_fmac_f32_e32 v48, v88, v94
	v_fmac_f32_e32 v48, v90, v92
	v_fmac_f32_e32 v48, v91, v93
	ds_read_b128 v[88:91], v100 offset:28672
	v_add_f32_e32 v49, 0, v48
	s_waitcnt lgkmcnt(0)
	v_mul_f32_e32 v48, v95, v89
	v_fmac_f32_e32 v48, v94, v88
	v_fmac_f32_e32 v48, v92, v90
	v_fmac_f32_e32 v48, v93, v91
	ds_read_b128 v[88:91], v100 offset:37888
	ds_read_b128 v[92:95], v84 offset:1024
	ds_read_b128 v[96:99], v83 offset:1024
	v_add_f32_e32 v48, 0, v48
	s_waitcnt lgkmcnt(2)
	v_pk_mul_f32 v[42:43], v[42:43], v[88:89]
	s_waitcnt lgkmcnt(1)
	v_pk_add_f32 v[88:89], v[92:93], 1.0 op_sel_hi:[1,0]
	v_pk_mul_f32 v[44:45], v[44:45], v[90:91]
	s_waitcnt lgkmcnt(0)
	v_pk_fma_f32 v[42:43], v[42:43], v[88:89], v[96:97]
	v_pk_add_f32 v[88:89], v[94:95], 1.0 op_sel_hi:[1,0]
	s_nop 0
	v_pk_fma_f32 v[44:45], v[44:45], v[88:89], v[98:99]
	v_cvt_pk_bf16_f32 v88, v42, v43
	v_cvt_pk_bf16_f32 v89, v44, v45
	global_store_dwordx2 v[46:47], v[88:89], off offset:512
	ds_read_b128 v[88:91], v100 offset:1024
	s_waitcnt lgkmcnt(0)
	v_mul_f32_e32 v89, v43, v89
	v_fmac_f32_e32 v89, v42, v88
	v_fmac_f32_e32 v89, v44, v90
	v_fmac_f32_e32 v89, v45, v91
	ds_read_b128 v[90:93], v100 offset:5120
	v_add_f32_e32 v88, v103, v89
	s_waitcnt lgkmcnt(0)
	v_mul_f32_e32 v89, v43, v91
	v_fmac_f32_e32 v89, v42, v90
	v_fmac_f32_e32 v89, v44, v92
	v_fmac_f32_e32 v89, v45, v93
	ds_read_b128 v[90:93], v100 offset:9216
	v_add_f32_e32 v89, v104, v89
	s_waitcnt lgkmcnt(0)
	v_mul_f32_e32 v91, v43, v91
	v_fmac_f32_e32 v91, v42, v90
	v_fmac_f32_e32 v91, v44, v92
	v_fmac_f32_e32 v91, v45, v93
	v_add_f32_e32 v98, v105, v91
	ds_read_b128 v[90:93], v100 offset:13312
	s_waitcnt lgkmcnt(0)
	v_mul_f32_e32 v91, v43, v91
	v_fmac_f32_e32 v91, v42, v90
	v_fmac_f32_e32 v91, v44, v92
	v_fmac_f32_e32 v91, v45, v93
	v_add_f32_e32 v87, v87, v91
	ds_read_b128 v[90:93], v100 offset:17408
	s_waitcnt lgkmcnt(0)
	v_mul_f32_e32 v91, v43, v91
	v_fmac_f32_e32 v91, v42, v90
	v_fmac_f32_e32 v91, v44, v92
	v_fmac_f32_e32 v91, v45, v93
	v_add_f32_e32 v86, v86, v91
	ds_read_b128 v[90:93], v100 offset:21504
	s_waitcnt lgkmcnt(0)
	v_mul_f32_e32 v91, v43, v91
	v_fmac_f32_e32 v91, v42, v90
	v_fmac_f32_e32 v91, v44, v92
	v_fmac_f32_e32 v91, v45, v93
	v_add_f32_e32 v85, v85, v91
	ds_read_b128 v[90:93], v100 offset:25600
	s_waitcnt lgkmcnt(0)
	v_mul_f32_e32 v91, v43, v91
	v_fmac_f32_e32 v91, v42, v90
	v_fmac_f32_e32 v91, v44, v92
	v_fmac_f32_e32 v91, v45, v93
	v_add_f32_e32 v99, v49, v91
	ds_read_b128 v[90:93], v100 offset:29696
	s_waitcnt lgkmcnt(0)
	v_mul_f32_e32 v43, v43, v91
	v_fmac_f32_e32 v43, v42, v90
	v_fmac_f32_e32 v43, v44, v92
	v_fmac_f32_e32 v43, v45, v93
	v_add_f32_e32 v103, v48, v43
	ds_read_b128 v[42:45], v100 offset:38912
	ds_read_b128 v[90:93], v84 offset:2048
	ds_read_b128 v[94:97], v83 offset:2048
	s_waitcnt lgkmcnt(2)
	v_pk_mul_f32 v[38:39], v[38:39], v[42:43]
	s_waitcnt lgkmcnt(1)
	v_pk_add_f32 v[42:43], v[90:91], 1.0 op_sel_hi:[1,0]
	s_waitcnt lgkmcnt(0)
	v_pk_fma_f32 v[48:49], v[38:39], v[42:43], v[94:95]
	v_pk_mul_f32 v[38:39], v[40:41], v[76:77] op_sel_hi:[1,0]
	v_pk_add_f32 v[40:41], v[92:93], 1.0 op_sel_hi:[1,0]
	v_pk_mul_f32 v[38:39], v[38:39], v[44:45]
	s_nop 0
	v_pk_fma_f32 v[44:45], v[38:39], v[40:41], v[96:97]
	v_cvt_pk_bf16_f32 v38, v48, v49
	v_cvt_pk_bf16_f32 v39, v44, v45
	global_store_dwordx2 v[46:47], v[38:39], off offset:1024
	ds_read_b128 v[38:41], v100 offset:2048
	s_waitcnt lgkmcnt(0)
	v_mul_f32_e32 v39, v49, v39
	v_fmac_f32_e32 v39, v48, v38
	v_fmac_f32_e32 v39, v44, v40
	v_fmac_f32_e32 v39, v45, v41
	v_add_f32_e32 v43, v88, v39
	ds_read_b128 v[38:41], v100 offset:6144
	s_waitcnt lgkmcnt(0)
	v_mul_f32_e32 v39, v49, v39
	v_fmac_f32_e32 v39, v48, v38
	v_fmac_f32_e32 v39, v44, v40
	v_fmac_f32_e32 v39, v45, v41
	v_add_f32_e32 v104, v89, v39
	ds_read_b128 v[38:41], v100 offset:10240
	s_waitcnt lgkmcnt(0)
	v_mul_f32_e32 v39, v49, v39
	v_fmac_f32_e32 v39, v48, v38
	v_fmac_f32_e32 v39, v44, v40
	v_fmac_f32_e32 v39, v45, v41
	v_add_f32_e32 v98, v98, v39
	ds_read_b128 v[38:41], v100 offset:14336
	s_waitcnt lgkmcnt(0)
	v_mul_f32_e32 v39, v49, v39
	v_fmac_f32_e32 v39, v48, v38
	v_fmac_f32_e32 v39, v44, v40
	v_fmac_f32_e32 v39, v45, v41
	v_add_f32_e32 v42, v87, v39
	ds_read_b128 v[38:41], v100 offset:18432
	s_waitcnt lgkmcnt(0)
	v_mul_f32_e32 v39, v49, v39
	v_fmac_f32_e32 v39, v48, v38
	v_fmac_f32_e32 v39, v44, v40
	v_fmac_f32_e32 v39, v45, v41
	v_add_f32_e32 v41, v86, v39
	ds_read_b128 v[86:89], v100 offset:22528
	s_waitcnt lgkmcnt(0)
	v_mul_f32_e32 v38, v49, v87
	v_fmac_f32_e32 v38, v48, v86
	v_fmac_f32_e32 v38, v44, v88
	v_fmac_f32_e32 v38, v45, v89
	ds_read_b128 v[86:89], v100 offset:26624
	v_add_f32_e32 v40, v85, v38
	s_waitcnt lgkmcnt(0)
	v_mul_f32_e32 v38, v49, v87
	v_fmac_f32_e32 v38, v48, v86
	v_fmac_f32_e32 v38, v44, v88
	v_fmac_f32_e32 v38, v45, v89
	ds_read_b128 v[86:89], v100 offset:30720
	v_add_f32_e32 v39, v99, v38
	s_waitcnt lgkmcnt(0)
	v_mul_f32_e32 v38, v49, v87
	v_fmac_f32_e32 v38, v48, v86
	v_fmac_f32_e32 v38, v44, v88
	v_fmac_f32_e32 v38, v45, v89
	ds_read_b128 v[86:89], v100 offset:39936
	ds_read_b128 v[90:93], v84 offset:3072
	ds_read_b128 v[94:97], v83 offset:3072
	v_add_f32_e32 v38, v103, v38
	s_waitcnt lgkmcnt(2)
	v_pk_mul_f32 v[34:35], v[34:35], v[86:87]
	s_waitcnt lgkmcnt(1)
	v_pk_add_f32 v[44:45], v[90:91], 1.0 op_sel_hi:[1,0]
	v_pk_mul_f32 v[36:37], v[36:37], v[88:89]
	s_waitcnt lgkmcnt(0)
	v_pk_fma_f32 v[34:35], v[34:35], v[44:45], v[94:95]
	v_pk_add_f32 v[44:45], v[92:93], 1.0 op_sel_hi:[1,0]
	s_nop 0
	v_pk_fma_f32 v[36:37], v[36:37], v[44:45], v[96:97]
	v_cvt_pk_bf16_f32 v44, v34, v35
	v_cvt_pk_bf16_f32 v45, v36, v37
	global_store_dwordx2 v[46:47], v[44:45], off offset:1536
	ds_read_b128 v[44:47], v100 offset:3072
	s_waitcnt lgkmcnt(0)
	v_mul_f32_e32 v45, v35, v45
	v_fmac_f32_e32 v45, v34, v44
	v_fmac_f32_e32 v45, v36, v46
	v_fmac_f32_e32 v45, v37, v47
	v_add_f32_e32 v43, v43, v45
	ds_read_b128 v[44:47], v100 offset:7168
	s_waitcnt lgkmcnt(0)
	v_mul_f32_e32 v45, v35, v45
	v_fmac_f32_e32 v45, v34, v44
	v_fmac_f32_e32 v45, v36, v46
	v_fmac_f32_e32 v45, v37, v47
	v_add_f32_e32 v48, v104, v45
	ds_read_b128 v[44:47], v100 offset:11264
	s_waitcnt lgkmcnt(0)
	v_mul_f32_e32 v45, v35, v45
	v_fmac_f32_e32 v45, v34, v44
	v_fmac_f32_e32 v45, v36, v46
	v_fmac_f32_e32 v45, v37, v47
	v_add_f32_e32 v49, v98, v45
	ds_read_b128 v[44:47], v100 offset:15360
	s_waitcnt lgkmcnt(0)
	v_mul_f32_e32 v45, v35, v45
	v_fmac_f32_e32 v45, v34, v44
	v_fmac_f32_e32 v45, v36, v46
	v_fmac_f32_e32 v45, v37, v47
	v_add_f32_e32 v42, v42, v45
	ds_read_b128 v[44:47], v100 offset:19456
	s_waitcnt lgkmcnt(0)
	v_mul_f32_e32 v45, v35, v45
	v_fmac_f32_e32 v45, v34, v44
	v_fmac_f32_e32 v45, v36, v46
	v_fmac_f32_e32 v45, v37, v47
	v_add_f32_e32 v41, v41, v45
	ds_read_b128 v[44:47], v100 offset:23552
	s_waitcnt lgkmcnt(0)
	v_mul_f32_e32 v45, v35, v45
	v_fmac_f32_e32 v45, v34, v44
	v_fmac_f32_e32 v45, v36, v46
	v_fmac_f32_e32 v45, v37, v47
	v_add_f32_e32 v40, v40, v45
	ds_read_b128 v[44:47], v100 offset:27648
	s_waitcnt lgkmcnt(0)
	v_mul_f32_e32 v45, v35, v45
	v_fmac_f32_e32 v45, v34, v44
	v_fmac_f32_e32 v45, v36, v46
	v_fmac_f32_e32 v45, v37, v47
	v_add_f32_e32 v39, v39, v45
	ds_read_b128 v[44:47], v100 offset:31744
	s_waitcnt lgkmcnt(0)
	v_mul_f32_e32 v35, v35, v45
	v_fmac_f32_e32 v35, v34, v44
	v_fmac_f32_e32 v35, v36, v46
	v_cndmask_b32_e64 v36, v43, v41, s[40:41]
	v_fmac_f32_e32 v35, v37, v47
	ds_bpermute_b32 v36, v249, v36
	v_cndmask_b32_e64 v37, v48, v40, s[40:41]
	v_add_f32_e32 v34, v38, v35
	ds_bpermute_b32 v37, v249, v37
	v_cndmask_b32_e64 v38, v49, v39, s[40:41]
	ds_bpermute_b32 v38, v249, v38
	v_cndmask_b32_e64 v35, v41, v43, s[40:41]
	s_waitcnt lgkmcnt(2)
	v_add_f32_e32 v35, v35, v36
	v_cndmask_b32_e64 v36, v40, v48, s[40:41]
	s_waitcnt lgkmcnt(1)
	v_add_f32_e32 v36, v36, v37
	v_cndmask_b32_e64 v37, v39, v49, s[40:41]
	s_waitcnt lgkmcnt(0)
	v_add_f32_e32 v37, v37, v38
	v_cndmask_b32_e64 v38, v34, v42, s[40:41]
	v_cndmask_b32_e64 v34, v42, v34, s[40:41]
	ds_bpermute_b32 v34, v249, v34
	s_waitcnt lgkmcnt(0)
	v_add_f32_e32 v34, v38, v34
	v_cndmask_b32_e64 v38, v37, v35, s[42:43]
	v_cndmask_b32_e64 v35, v35, v37, s[42:43]
	v_cndmask_b32_e64 v37, v34, v36, s[42:43]
	v_cndmask_b32_e64 v34, v36, v34, s[42:43]
	ds_bpermute_b32 v35, v248, v35
	ds_bpermute_b32 v34, v248, v34
	s_waitcnt lgkmcnt(1)
	v_add_f32_e32 v35, v38, v35
	s_waitcnt lgkmcnt(0)
	v_add_f32_e32 v34, v37, v34
	v_cndmask_b32_e64 v36, v34, v35, s[44:45]
	v_cndmask_b32_e64 v34, v35, v34, s[44:45]
	s_nop 1
	v_mov_b32_dpp v34, v34 row_ror:8 row_mask:0xf bank_mask:0xf
	s_waitcnt lgkmcnt(0)
	v_add_f32_e32 v34, v36, v34
	s_nop 1
	v_mov_b32_dpp v35, v34 row_half_mirror row_mask:0xf bank_mask:0xf
	s_nop 1
	v_mov_b32_dpp v35, v35 quad_perm:[3,2,1,0] row_mask:0xf bank_mask:0xf
	s_waitcnt lgkmcnt(0)
	v_add_f32_e32 v34, v34, v35
	s_nop 1
	v_mov_b32_dpp v35, v34 quad_perm:[2,3,0,1] row_mask:0xf bank_mask:0xf
	s_waitcnt lgkmcnt(0)
	v_add_f32_e32 v34, v34, v35
	ds_bpermute_b32 v35, v244, v34
	s_and_saveexec_b64 s[18:19], s[46:47]
	s_cbranch_execz .LBB0_450
	s_lshl_b64 s[2:3], s[52:53], 5
	s_waitcnt lgkmcnt(0)
	v_add_f32_e32 v36, v34, v35
	v_lshl_add_u64 v[34:35], v[64:65], 0, s[2:3]
	global_store_dword v[34:35], v36, off
	s_branch .LBB0_450
